# XCD-local barriers for seams 7,8,12,13 (dependencies stay within a wg%8 group; run-time check of group->XCC placement with fallback to the grid barrier) on top of attention/pool_run changes
# speedup vs baseline: 1.0395x; 1.0063x over previous
.LBB0_5:
	s_or_b64 exec, exec, s[6:7]
	s_cmp_gt_u32 s2, 7
	s_cbranch_scc1 .Lxpub_skip
	s_and_saveexec_b64 s[6:7], s[10:11]
	s_lshl_b32 s3, s2, 2
	s_add_i32 s3, s3, 0x3d68
	v_mov_b32_e32 v2, s3
	v_mov_b32_e32 v1, s33
	global_store_dword v2, v1, s[88:89] sc0 sc1
	s_or_b64 exec, exec, s[6:7]
.Lxpub_skip:
	s_cmpk_lt_i32 s75, 0x3e9
	s_cbranch_scc1 .LBB0_17
	v_lshrrev_b32_e32 v1, 20, v0
	v_lshrrev_b32_e32 v0, 10, v0
	v_or_b32_e32 v0, v0, v1
	s_movk_i32 s3, 0x3ff
	v_and_or_b32 v0, v0, s3, v192
	v_cmp_eq_u32_e32 vcc, 0, v0
	s_barrier
	s_and_saveexec_b64 s[6:7], vcc
	s_cbranch_execz .LBB0_16
	buffer_wbl2 sc1
	s_waitcnt vmcnt(0)
	s_load_dwordx2 s[8:9], s[8:9], 0x58
	v_mov_b32_e32 v2, 0
	s_mov_b64 s[12:13], exec
	v_mbcnt_lo_u32_b32 v1, s12, 0
	v_mbcnt_hi_u32_b32 v1, s13, v1
	s_waitcnt lgkmcnt(0)
	global_load_dword v0, v2, s[8:9] offset:40
	v_cmp_eq_u32_e32 vcc, 0, v1
	s_and_saveexec_b64 s[14:15], vcc
	s_cbranch_execz .LBB0_9
	s_bcnt1_i32_b64 s3, s[12:13]
	v_mov_b32_e32 v3, s3
	global_atomic_add v3, v2, v3, s[8:9] offset:32 sc0

.LBB0_334:
	s_and_saveexec_b64 s[6:7], s[10:11]
	s_cbranch_execz .Lxchk_done
	s_and_b32 s3, s2, 7
	s_lshl_b32 s3, s3, 2
	s_add_i32 s3, s3, 0x3d68
	v_mov_b32_e32 v2, s3
	global_load_dword v1, v2, s[88:89] sc1
	s_waitcnt vmcnt(0)
	v_cmp_ne_u32_e32 vcc, s33, v1
	s_and_b64 exec, exec, vcc
	s_cbranch_execz .Lxchk_done
	v_mov_b32_e32 v2, 0x3d90
	v_mov_b32_e32 v1, 1
	global_atomic_add v2, v1, s[88:89]
.Lxchk_done:
	s_or_b64 exec, exec, s[6:7]
	s_cmp_lt_i32 s74, 2
	s_cselect_b64 s[8:9], -1, 0
	s_and_b64 s[0:1], s[8:9], s[0:1]
	s_andn2_b64 vcc, exec, s[0:1]
	s_cbranch_vccnz .LBB0_424
	s_abs_i32 s0, s34
	v_cvt_f32_u32_e32 v0, s0
	s_add_i32 s1, s34, 0x3ff
	s_sub_i32 s3, 0xfffffc01, s34
	s_xor_b32 s6, s1, s34
	v_rcp_iflag_f32_e32 v0, v0
	s_max_i32 s1, s1, s3
	s_sub_i32 s3, 0, s0
	s_ashr_i32 s6, s6, 31
	v_mul_f32_e32 v0, 0x4f7ffffe, v0
	v_cvt_u32_f32_e32 v0, v0
	s_nop 0
	v_readfirstlane_b32 s7, v0
	s_mul_i32 s3, s3, s7
	s_mul_hi_u32 s3, s7, s3
	s_add_i32 s7, s7, s3
	s_mul_hi_u32 s3, s1, s7
	s_mul_i32 s7, s3, s0
	s_sub_i32 s1, s1, s7
	s_add_i32 s12, s3, 1
	s_sub_i32 s7, s1, s0
	s_cmp_ge_u32 s1, s0
	s_cselect_b32 s3, s12, s3
	s_cselect_b32 s1, s7, s1
	s_add_i32 s7, s3, 1
	s_cmp_ge_u32 s1, s0
	s_cselect_b32 s0, s7, s3
	s_xor_b32 s0, s0, s6
	s_sub_i32 s3, s0, s6
	s_cmp_gt_i32 s3, 0
	s_cselect_b64 s[0:1], -1, 0
	s_cmpk_lt_i32 s2, 0x400
	s_cselect_b64 s[6:7], -1, 0
	s_and_b64 s[6:7], s[6:7], s[0:1]
	v_cndmask_b32_e64 v0, 0, 1, s[6:7]
	v_cmp_ne_u32_e64 s[0:1], 1, v0
	s_andn2_b64 vcc, exec, s[6:7]
	v_readfirstlane_b32 s12, v192
	s_cbranch_vccnz .LBB0_341
	s_ashr_i32 s6, s2, 31
	s_lshr_b32 s6, s6, 29
	s_add_i32 s13, s2, s6
	s_and_b32 s6, s13, -8
	s_sub_i32 s14, s2, s6
	s_cmp_gt_i32 s14, -1
	s_cbranch_scc0 .LBB0_338
	s_lshl_b32 s15, s14, 7
	s_cbranch_execz .LBB0_339
	s_branch .LBB0_340

.LBB0_478:
	v_mov_b32_e32 v0, 0x3d90
	global_load_dword v0, v0, s[88:89] sc1
	s_waitcnt vmcnt(0)
	v_readfirstlane_b32 s99, v0
	s_cmp_lt_i32 s74, 3
	s_cselect_b64 s[6:7], -1, 0
	s_and_b64 s[0:1], s[6:7], s[0:1]
	s_andn2_b64 vcc, exec, s[0:1]
	s_cbranch_vccnz .LBB0_668
	s_add_u32 s42, s72, 0x4813600
	s_addc_u32 s43, s73, 0
	s_waitcnt lgkmcnt(0)
	s_add_u32 s16, s72, 0x12940000
	v_lshrrev_b32_e32 v127, 1, v192
	s_addc_u32 s17, s73, 0
	v_and_b32_e32 v156, 24, v127
	v_lshlrev_b32_e32 v0, 6, v192
	v_lshlrev_b32_e32 v1, 2, v192
	v_readfirstlane_b32 s12, v192
	v_lshlrev_b32_e32 v157, 1, v156
	v_and_b32_e32 v0, 0x3c0, v0
	s_cmpk_gt_i32 s2, 0x7f
	v_and_b32_e32 v1, 32, v1
	s_cbranch_scc0 .LBB0_481
	v_and_b32_e32 v14, 63, v192
	v_lshrrev_b32_e32 v160, 3, v192
	v_and_b32_e32 v158, 15, v192
	v_bitop3_b32 v159, v157, v1, v0 bitop3:0x36
	s_cbranch_execz .LBB0_482
	s_branch .LBB0_509

.LBB0_889:
	s_andn2_saveexec_b64 s[8:9], s[8:9]
	s_cbranch_execz .LBB0_909
	s_mov_b64 s[8:9], exec
	buffer_wbl2 sc1
	s_waitcnt lgkmcnt(0)
	s_waitcnt vmcnt(0)
	s_cmp_eq_u32 s99, 0
	s_cbranch_scc1 .LBB0_906
	v_mbcnt_lo_u32_b32 v1, s8, 0
	v_mbcnt_hi_u32_b32 v1, s9, v1
	v_cmp_eq_u32_e32 vcc, 0, v1
	s_and_saveexec_b64 s[14:15], vcc
	s_cbranch_execz .LBB0_892
	s_bcnt1_i32_b64 s3, s[8:9]
	v_mov_b32_e32 v2, 0x4813000
	v_mov_b32_e32 v3, s3
	global_atomic_add v2, v2, v3, s[72:73] offset:1024 sc0

.LBB0_1021:
	s_andn2_saveexec_b64 s[8:9], s[8:9]
	s_cbranch_execz .LBB0_1041
	s_mov_b64 s[8:9], exec
	buffer_wbl2 sc1
	s_waitcnt lgkmcnt(0)
	s_waitcnt vmcnt(0)
	s_cmp_eq_u32 s99, 0
	s_cbranch_scc1 .LBB0_1038
	v_mbcnt_lo_u32_b32 v1, s8, 0
	v_mbcnt_hi_u32_b32 v1, s9, v1
	v_cmp_eq_u32_e32 vcc, 0, v1
	s_and_saveexec_b64 s[16:17], vcc
	s_cbranch_execz .LBB0_1024
	s_bcnt1_i32_b64 s3, s[8:9]
	v_mov_b32_e32 v2, 0x4813000
	v_mov_b32_e32 v3, s3
	global_atomic_add v2, v2, v3, s[72:73] offset:1024 sc0

.LBB0_1467:
	s_andn2_saveexec_b64 s[8:9], s[8:9]
	s_cbranch_execz .LBB0_1487
	s_mov_b64 s[8:9], exec
	buffer_wbl2 sc1
	s_waitcnt lgkmcnt(0)
	s_waitcnt vmcnt(0)
	s_cmp_eq_u32 s99, 0
	s_cbranch_scc1 .LBB0_1484
	v_mbcnt_lo_u32_b32 v1, s8, 0
	v_mbcnt_hi_u32_b32 v1, s9, v1
	v_cmp_eq_u32_e32 vcc, 0, v1
	s_and_saveexec_b64 s[10:11], vcc
	s_cbranch_execz .LBB0_1470
	s_bcnt1_i32_b64 s3, s[8:9]
	v_mov_b32_e32 v2, 0x4813000
	v_mov_b32_e32 v3, s3
	global_atomic_add v2, v2, v3, s[72:73] offset:1024 sc0

	.amdhsa_kernel _Z10fwd_kernel4Args
		.amdhsa_group_segment_fixed_size 0
		.amdhsa_private_segment_fixed_size 0
		.amdhsa_kernarg_size 480
		.amdhsa_user_sgpr_count 2
		.amdhsa_user_sgpr_dispatch_ptr 0
		.amdhsa_user_sgpr_queue_ptr 0
		.amdhsa_user_sgpr_kernarg_segment_ptr 1
		.amdhsa_user_sgpr_dispatch_id 0
		.amdhsa_user_sgpr_kernarg_preload_length 0
		.amdhsa_user_sgpr_kernarg_preload_offset 0
		.amdhsa_user_sgpr_private_segment_size 0
		.amdhsa_uses_dynamic_stack 0
		.amdhsa_enable_private_segment 0
		.amdhsa_system_sgpr_workgroup_id_x 1
		.amdhsa_system_sgpr_workgroup_id_y 0
		.amdhsa_system_sgpr_workgroup_id_z 0
		.amdhsa_system_sgpr_workgroup_info 0
		.amdhsa_system_vgpr_workitem_id 2
		.amdhsa_next_free_vgpr 243
		.amdhsa_next_free_sgpr 102
		.amdhsa_accum_offset 244
		.amdhsa_reserve_vcc 1
		.amdhsa_float_round_mode_32 0
		.amdhsa_float_round_mode_16_64 0
		.amdhsa_float_denorm_mode_32 3
		.amdhsa_float_denorm_mode_16_64 3
		.amdhsa_dx10_clamp 1
		.amdhsa_ieee_mode 1
		.amdhsa_fp16_overflow 0
		.amdhsa_tg_split 0
		.amdhsa_exception_fp_ieee_invalid_op 0
		.amdhsa_exception_fp_denorm_src 0
		.amdhsa_exception_fp_ieee_div_zero 0
		.amdhsa_exception_fp_ieee_overflow 0
		.amdhsa_exception_fp_ieee_underflow 0
		.amdhsa_exception_fp_ieee_inexact 0
		.amdhsa_exception_int_div_zero 0
	.end_amdhsa_kernel

amdhsa.kernels:
  - .agpr_count:     0
    .args:
      - .offset:         0
        .size:           224
        .value_kind:     by_value
      - .offset:         224
        .size:           4
        .value_kind:     hidden_block_count_x
      - .offset:         228
        .size:           4
        .value_kind:     hidden_block_count_y
      - .offset:         232
        .size:           4
        .value_kind:     hidden_block_count_z
      - .offset:         236
        .size:           2
        .value_kind:     hidden_group_size_x
      - .offset:         238
        .size:           2
        .value_kind:     hidden_group_size_y
      - .offset:         240
        .size:           2
        .value_kind:     hidden_group_size_z
      - .offset:         242
        .size:           2
        .value_kind:     hidden_remainder_x
      - .offset:         244
        .size:           2
        .value_kind:     hidden_remainder_y
      - .offset:         246
        .size:           2
        .value_kind:     hidden_remainder_z
      - .offset:         264
        .size:           8
        .value_kind:     hidden_global_offset_x
      - .offset:         272
        .size:           8
        .value_kind:     hidden_global_offset_y
      - .offset:         280
        .size:           8
        .value_kind:     hidden_global_offset_z
      - .offset:         288
        .size:           2
        .value_kind:     hidden_grid_dims
      - .offset:         312
        .size:           8
        .value_kind:     hidden_multigrid_sync_arg
      - .offset:         344
        .size:           4
        .value_kind:     hidden_dynamic_lds_size
    .group_segment_fixed_size: 0
    .kernarg_segment_align: 8
    .kernarg_segment_size: 480
    .language:       OpenCL C
    .language_version:
      - 2
      - 0
    .max_flat_workgroup_size: 512
    .name:           _Z10fwd_kernel4Args
    .private_segment_fixed_size: 0
    .sgpr_count:     108
    .sgpr_spill_count: 15
    .symbol:         _Z10fwd_kernel4Args.kd
    .uniform_work_group_size: 1
    .uses_dynamic_stack: false
    .vgpr_count:     243
    .vgpr_spill_count: 0
    .wavefront_size: 64
